# norm2 (modulated RMSNorm before the FFN): rows processed in blocks of 4 with all loads issued up front and the six cross-lane reduction steps interleaved over the 4 rows
# speedup vs baseline: 1.0116x; 1.0116x over previous
.LBB0_816:
	s_or_b64 exec, exec, s[14:15]
	s_barrier
	ds_read_b128 v[0:3], v24
	ds_read_b128 v[4:7], v24 offset:16
	ds_read_b128 v[8:11], v24 offset:4096
	ds_read_b128 v[12:15], v24 offset:4112
	ds_read_b128 v[42:45], v24 offset:2048
	ds_read_b128 v[46:49], v24 offset:2064
	ds_read_b128 v[50:53], v24 offset:6144
	ds_read_b128 v[54:57], v24 offset:6160
	v_readfirstlane_b32 s92, v22
	v_readfirstlane_b32 s93, v23
	v_readfirstlane_b32 s94, v20
	v_readfirstlane_b32 s95, v21
	v_and_b32_e32 v82, 63, v196
	v_lshlrev_b32_e32 v82, 4, v82
	s_nop 1
	s_add_u32 s94, s94, 0x5200e00
	s_addc_u32 s95, s95, 0
	s_mov_b32 s71, 8
	s_waitcnt lgkmcnt(0)
.Ln2_loop:
	global_load_dwordx4 v[84:87], v82, s[92:93] offset:0
	global_load_dwordx4 v[88:91], v82, s[92:93] offset:1024
	global_load_dwordx4 v[112:115], v82, s[92:93] offset:2048
	global_load_dwordx4 v[116:119], v82, s[92:93] offset:3072
	s_add_u32 s92, s92, 0x1000
	s_addc_u32 s93, s93, 0
	global_load_dwordx4 v[140:143], v82, s[92:93] offset:0
	global_load_dwordx4 v[144:147], v82, s[92:93] offset:1024
	global_load_dwordx4 v[168:171], v82, s[92:93] offset:2048
	global_load_dwordx4 v[172:175], v82, s[92:93] offset:3072
	s_add_u32 s92, s92, 0x1000
	s_addc_u32 s93, s93, 0
	s_waitcnt vmcnt(0)
	v_lshlrev_b32_e32 v92, 16, v84
	v_and_b32_e32 v93, 0xffff0000, v84
	v_lshlrev_b32_e32 v94, 16, v85
	v_and_b32_e32 v95, 0xffff0000, v85
	v_lshlrev_b32_e32 v96, 16, v86
	v_and_b32_e32 v97, 0xffff0000, v86
	v_lshlrev_b32_e32 v98, 16, v87
	v_and_b32_e32 v99, 0xffff0000, v87
	v_lshlrev_b32_e32 v100, 16, v88
	v_and_b32_e32 v101, 0xffff0000, v88
	v_lshlrev_b32_e32 v102, 16, v89
	v_and_b32_e32 v103, 0xffff0000, v89
	v_lshlrev_b32_e32 v104, 16, v90
	v_and_b32_e32 v105, 0xffff0000, v90
	v_lshlrev_b32_e32 v106, 16, v91
	v_and_b32_e32 v107, 0xffff0000, v91
	v_mul_f32_e32 v198, v93, v93
	v_mul_f32_e32 v199, v97, v97
	v_mul_f32_e32 v200, v105, v105
	v_mul_f32_e32 v201, v101, v101
	v_fma_f32 v198, v92, v92, v198
	v_fma_f32 v199, v96, v96, v199
	v_fma_f32 v200, v104, v104, v200
	v_fma_f32 v201, v100, v100, v201
	v_fma_f32 v198, v94, v94, v198
	v_fma_f32 v199, v98, v98, v199
	v_fma_f32 v200, v106, v106, v200
	v_fma_f32 v201, v102, v102, v201
	v_fma_f32 v198, v95, v95, v198
	v_fma_f32 v199, v99, v99, v199
	v_fma_f32 v200, v107, v107, v200
	v_fma_f32 v201, v103, v103, v201
	v_add_f32_e32 v108, v198, v199
	v_add_f32_e32 v108, v108, v201
	v_add_f32_e32 v108, v200, v108
	v_lshlrev_b32_e32 v120, 16, v112
	v_and_b32_e32 v121, 0xffff0000, v112
	v_lshlrev_b32_e32 v122, 16, v113
	v_and_b32_e32 v123, 0xffff0000, v113
	v_lshlrev_b32_e32 v124, 16, v114
	v_and_b32_e32 v125, 0xffff0000, v114
	v_lshlrev_b32_e32 v126, 16, v115
	v_and_b32_e32 v127, 0xffff0000, v115
	v_lshlrev_b32_e32 v128, 16, v116
	v_and_b32_e32 v129, 0xffff0000, v116
	v_lshlrev_b32_e32 v130, 16, v117
	v_and_b32_e32 v131, 0xffff0000, v117
	v_lshlrev_b32_e32 v132, 16, v118
	v_and_b32_e32 v133, 0xffff0000, v118
	v_lshlrev_b32_e32 v134, 16, v119
	v_and_b32_e32 v135, 0xffff0000, v119
	v_mul_f32_e32 v202, v121, v121
	v_mul_f32_e32 v203, v125, v125
	v_mul_f32_e32 v204, v133, v133
	v_mul_f32_e32 v205, v129, v129
	v_fma_f32 v202, v120, v120, v202
	v_fma_f32 v203, v124, v124, v203
	v_fma_f32 v204, v132, v132, v204
	v_fma_f32 v205, v128, v128, v205
	v_fma_f32 v202, v122, v122, v202
	v_fma_f32 v203, v126, v126, v203
	v_fma_f32 v204, v134, v134, v204
	v_fma_f32 v205, v130, v130, v205
	v_fma_f32 v202, v123, v123, v202
	v_fma_f32 v203, v127, v127, v203
	v_fma_f32 v204, v135, v135, v204
	v_fma_f32 v205, v131, v131, v205
	v_add_f32_e32 v136, v202, v203
	v_add_f32_e32 v136, v136, v205
	v_add_f32_e32 v136, v204, v136
	v_lshlrev_b32_e32 v148, 16, v140
	v_and_b32_e32 v149, 0xffff0000, v140
	v_lshlrev_b32_e32 v150, 16, v141
	v_and_b32_e32 v151, 0xffff0000, v141
	v_lshlrev_b32_e32 v152, 16, v142
	v_and_b32_e32 v153, 0xffff0000, v142
	v_lshlrev_b32_e32 v154, 16, v143
	v_and_b32_e32 v155, 0xffff0000, v143
	v_lshlrev_b32_e32 v156, 16, v144
	v_and_b32_e32 v157, 0xffff0000, v144
	v_lshlrev_b32_e32 v158, 16, v145
	v_and_b32_e32 v159, 0xffff0000, v145
	v_lshlrev_b32_e32 v160, 16, v146
	v_and_b32_e32 v161, 0xffff0000, v146
	v_lshlrev_b32_e32 v162, 16, v147
	v_and_b32_e32 v163, 0xffff0000, v147
	v_mul_f32_e32 v206, v149, v149
	v_mul_f32_e32 v207, v153, v153
	v_mul_f32_e32 v208, v161, v161
	v_mul_f32_e32 v209, v157, v157
	v_fma_f32 v206, v148, v148, v206
	v_fma_f32 v207, v152, v152, v207
	v_fma_f32 v208, v160, v160, v208
	v_fma_f32 v209, v156, v156, v209
	v_fma_f32 v206, v150, v150, v206
	v_fma_f32 v207, v154, v154, v207
	v_fma_f32 v208, v162, v162, v208
	v_fma_f32 v209, v158, v158, v209
	v_fma_f32 v206, v151, v151, v206
	v_fma_f32 v207, v155, v155, v207
	v_fma_f32 v208, v163, v163, v208
	v_fma_f32 v209, v159, v159, v209
	v_add_f32_e32 v164, v206, v207
	v_add_f32_e32 v164, v164, v209
	v_add_f32_e32 v164, v208, v164
	v_lshlrev_b32_e32 v176, 16, v168
	v_and_b32_e32 v177, 0xffff0000, v168
	v_lshlrev_b32_e32 v178, 16, v169
	v_and_b32_e32 v179, 0xffff0000, v169
	v_lshlrev_b32_e32 v180, 16, v170
	v_and_b32_e32 v181, 0xffff0000, v170
	v_lshlrev_b32_e32 v182, 16, v171
	v_and_b32_e32 v183, 0xffff0000, v171
	v_lshlrev_b32_e32 v184, 16, v172
	v_and_b32_e32 v185, 0xffff0000, v172
	v_lshlrev_b32_e32 v186, 16, v173
	v_and_b32_e32 v187, 0xffff0000, v173
	v_lshlrev_b32_e32 v188, 16, v174
	v_and_b32_e32 v189, 0xffff0000, v174
	v_lshlrev_b32_e32 v190, 16, v175
	v_and_b32_e32 v191, 0xffff0000, v175
	v_mul_f32_e32 v210, v177, v177
	v_mul_f32_e32 v211, v181, v181
	v_mul_f32_e32 v212, v189, v189
	v_mul_f32_e32 v213, v185, v185
	v_fma_f32 v210, v176, v176, v210
	v_fma_f32 v211, v180, v180, v211
	v_fma_f32 v212, v188, v188, v212
	v_fma_f32 v213, v184, v184, v213
	v_fma_f32 v210, v178, v178, v210
	v_fma_f32 v211, v182, v182, v211
	v_fma_f32 v212, v190, v190, v212
	v_fma_f32 v213, v186, v186, v213
	v_fma_f32 v210, v179, v179, v210
	v_fma_f32 v211, v183, v183, v211
	v_fma_f32 v212, v191, v191, v212
	v_fma_f32 v213, v187, v187, v213
	v_add_f32_e32 v192, v210, v211
	v_add_f32_e32 v192, v192, v213
	v_add_f32_e32 v192, v212, v192
	ds_bpermute_b32 v109, v25, v108
	ds_bpermute_b32 v137, v25, v136
	ds_bpermute_b32 v165, v25, v164
	ds_bpermute_b32 v193, v25, v192
	s_waitcnt lgkmcnt(0)
	v_add_f32_e32 v108, v108, v109
	v_add_f32_e32 v136, v136, v137
	v_add_f32_e32 v164, v164, v165
	v_add_f32_e32 v192, v192, v193
	ds_bpermute_b32 v109, v26, v108
	ds_bpermute_b32 v137, v26, v136
	ds_bpermute_b32 v165, v26, v164
	ds_bpermute_b32 v193, v26, v192
	s_waitcnt lgkmcnt(0)
	v_add_f32_e32 v108, v108, v109
	v_add_f32_e32 v136, v136, v137
	v_add_f32_e32 v164, v164, v165
	v_add_f32_e32 v192, v192, v193
	ds_bpermute_b32 v109, v27, v108
	ds_bpermute_b32 v137, v27, v136
	ds_bpermute_b32 v165, v27, v164
	ds_bpermute_b32 v193, v27, v192
	s_waitcnt lgkmcnt(0)
	v_add_f32_e32 v108, v108, v109
	v_add_f32_e32 v136, v136, v137
	v_add_f32_e32 v164, v164, v165
	v_add_f32_e32 v192, v192, v193
	ds_bpermute_b32 v109, v28, v108
	ds_bpermute_b32 v137, v28, v136
	ds_bpermute_b32 v165, v28, v164
	ds_bpermute_b32 v193, v28, v192
	s_waitcnt lgkmcnt(0)
	v_add_f32_e32 v108, v108, v109
	v_add_f32_e32 v136, v136, v137
	v_add_f32_e32 v164, v164, v165
	v_add_f32_e32 v192, v192, v193
	ds_bpermute_b32 v109, v29, v108
	ds_bpermute_b32 v137, v29, v136
	ds_bpermute_b32 v165, v29, v164
	ds_bpermute_b32 v193, v29, v192
	s_waitcnt lgkmcnt(0)
	v_add_f32_e32 v108, v108, v109
	v_add_f32_e32 v136, v136, v137
	v_add_f32_e32 v164, v164, v165
	v_add_f32_e32 v192, v192, v193
	ds_bpermute_b32 v109, v30, v108
	ds_bpermute_b32 v137, v30, v136
	ds_bpermute_b32 v165, v30, v164
	ds_bpermute_b32 v193, v30, v192
	s_waitcnt lgkmcnt(0)
	v_add_f32_e32 v108, v108, v109
	v_add_f32_e32 v136, v136, v137
	v_add_f32_e32 v164, v164, v165
	v_add_f32_e32 v192, v192, v193
	v_fmamk_f32 v108, v108, 0x3a800000, v33
	v_mul_f32_e32 v109, 0x4b800000, v108
	v_cmp_gt_f32_e32 vcc, s19, v108
	s_nop 1
	v_cndmask_b32_e32 v108, v108, v109, vcc
	v_rsq_f32_e32 v108, v108
	s_nop 0
	v_mul_f32_e32 v109, 0x45800000, v108
	v_cndmask_b32_e32 v110, v108, v109, vcc
	v_fmamk_f32 v136, v136, 0x3a800000, v33
	v_mul_f32_e32 v137, 0x4b800000, v136
	v_cmp_gt_f32_e32 vcc, s19, v136
	s_nop 1
	v_cndmask_b32_e32 v136, v136, v137, vcc
	v_rsq_f32_e32 v136, v136
	s_nop 0
	v_mul_f32_e32 v137, 0x45800000, v136
	v_cndmask_b32_e32 v138, v136, v137, vcc
	v_fmamk_f32 v164, v164, 0x3a800000, v33
	v_mul_f32_e32 v165, 0x4b800000, v164
	v_cmp_gt_f32_e32 vcc, s19, v164
	s_nop 1
	v_cndmask_b32_e32 v164, v164, v165, vcc
	v_rsq_f32_e32 v164, v164
	s_nop 0
	v_mul_f32_e32 v165, 0x45800000, v164
	v_cndmask_b32_e32 v166, v164, v165, vcc
	v_fmamk_f32 v192, v192, 0x3a800000, v33
	v_mul_f32_e32 v193, 0x4b800000, v192
	v_cmp_gt_f32_e32 vcc, s19, v192
	s_nop 1
	v_cndmask_b32_e32 v192, v192, v193, vcc
	v_rsq_f32_e32 v192, v192
	s_nop 0
	v_mul_f32_e32 v193, 0x45800000, v192
	v_cndmask_b32_e32 v194, v192, v193, vcc
	v_pk_mul_f32 v[92:93], v[92:93], v[110:111] op_sel_hi:[1,0]
	v_pk_mul_f32 v[94:95], v[94:95], v[110:111] op_sel_hi:[1,0]
	v_pk_mul_f32 v[96:97], v[96:97], v[110:111] op_sel_hi:[1,0]
	v_pk_mul_f32 v[98:99], v[98:99], v[110:111] op_sel_hi:[1,0]
	v_pk_mul_f32 v[100:101], v[100:101], v[110:111] op_sel_hi:[1,0]
	v_pk_mul_f32 v[102:103], v[102:103], v[110:111] op_sel_hi:[1,0]
	v_pk_mul_f32 v[104:105], v[104:105], v[110:111] op_sel_hi:[1,0]
	v_pk_mul_f32 v[106:107], v[106:107], v[110:111] op_sel_hi:[1,0]
	v_pk_fma_f32 v[92:93], v[0:1], v[92:93], v[8:9]
	v_pk_fma_f32 v[94:95], v[2:3], v[94:95], v[10:11]
	v_pk_fma_f32 v[96:97], v[4:5], v[96:97], v[12:13]
	v_pk_fma_f32 v[98:99], v[6:7], v[98:99], v[14:15]
	v_pk_fma_f32 v[100:101], v[42:43], v[100:101], v[50:51]
	v_pk_fma_f32 v[102:103], v[44:45], v[102:103], v[52:53]
	v_pk_fma_f32 v[104:105], v[46:47], v[104:105], v[54:55]
	v_pk_fma_f32 v[106:107], v[48:49], v[106:107], v[56:57]
	v_cvt_pk_bf16_f32 v84, v92, v93
	v_cvt_pk_bf16_f32 v85, v94, v95
	v_cvt_pk_bf16_f32 v86, v96, v97
	v_cvt_pk_bf16_f32 v87, v98, v99
	v_cvt_pk_bf16_f32 v88, v100, v101
	v_cvt_pk_bf16_f32 v89, v102, v103
	v_cvt_pk_bf16_f32 v90, v104, v105
	v_cvt_pk_bf16_f32 v91, v106, v107
	v_pk_mul_f32 v[120:121], v[120:121], v[138:139] op_sel_hi:[1,0]
	v_pk_mul_f32 v[122:123], v[122:123], v[138:139] op_sel_hi:[1,0]
	v_pk_mul_f32 v[124:125], v[124:125], v[138:139] op_sel_hi:[1,0]
	v_pk_mul_f32 v[126:127], v[126:127], v[138:139] op_sel_hi:[1,0]
	v_pk_mul_f32 v[128:129], v[128:129], v[138:139] op_sel_hi:[1,0]
	v_pk_mul_f32 v[130:131], v[130:131], v[138:139] op_sel_hi:[1,0]
	v_pk_mul_f32 v[132:133], v[132:133], v[138:139] op_sel_hi:[1,0]
	v_pk_mul_f32 v[134:135], v[134:135], v[138:139] op_sel_hi:[1,0]
	v_pk_fma_f32 v[120:121], v[0:1], v[120:121], v[8:9]
	v_pk_fma_f32 v[122:123], v[2:3], v[122:123], v[10:11]
	v_pk_fma_f32 v[124:125], v[4:5], v[124:125], v[12:13]
	v_pk_fma_f32 v[126:127], v[6:7], v[126:127], v[14:15]
	v_pk_fma_f32 v[128:129], v[42:43], v[128:129], v[50:51]
	v_pk_fma_f32 v[130:131], v[44:45], v[130:131], v[52:53]
	v_pk_fma_f32 v[132:133], v[46:47], v[132:133], v[54:55]
	v_pk_fma_f32 v[134:135], v[48:49], v[134:135], v[56:57]
	v_cvt_pk_bf16_f32 v112, v120, v121
	v_cvt_pk_bf16_f32 v113, v122, v123
	v_cvt_pk_bf16_f32 v114, v124, v125
	v_cvt_pk_bf16_f32 v115, v126, v127
	v_cvt_pk_bf16_f32 v116, v128, v129
	v_cvt_pk_bf16_f32 v117, v130, v131
	v_cvt_pk_bf16_f32 v118, v132, v133
	v_cvt_pk_bf16_f32 v119, v134, v135
	v_pk_mul_f32 v[148:149], v[148:149], v[166:167] op_sel_hi:[1,0]
	v_pk_mul_f32 v[150:151], v[150:151], v[166:167] op_sel_hi:[1,0]
	v_pk_mul_f32 v[152:153], v[152:153], v[166:167] op_sel_hi:[1,0]
	v_pk_mul_f32 v[154:155], v[154:155], v[166:167] op_sel_hi:[1,0]
	v_pk_mul_f32 v[156:157], v[156:157], v[166:167] op_sel_hi:[1,0]
	v_pk_mul_f32 v[158:159], v[158:159], v[166:167] op_sel_hi:[1,0]
	v_pk_mul_f32 v[160:161], v[160:161], v[166:167] op_sel_hi:[1,0]
	v_pk_mul_f32 v[162:163], v[162:163], v[166:167] op_sel_hi:[1,0]
	v_pk_fma_f32 v[148:149], v[0:1], v[148:149], v[8:9]
	v_pk_fma_f32 v[150:151], v[2:3], v[150:151], v[10:11]
	v_pk_fma_f32 v[152:153], v[4:5], v[152:153], v[12:13]
	v_pk_fma_f32 v[154:155], v[6:7], v[154:155], v[14:15]
	v_pk_fma_f32 v[156:157], v[42:43], v[156:157], v[50:51]
	v_pk_fma_f32 v[158:159], v[44:45], v[158:159], v[52:53]
	v_pk_fma_f32 v[160:161], v[46:47], v[160:161], v[54:55]
	v_pk_fma_f32 v[162:163], v[48:49], v[162:163], v[56:57]
	v_cvt_pk_bf16_f32 v140, v148, v149
	v_cvt_pk_bf16_f32 v141, v150, v151
	v_cvt_pk_bf16_f32 v142, v152, v153
	v_cvt_pk_bf16_f32 v143, v154, v155
	v_cvt_pk_bf16_f32 v144, v156, v157
	v_cvt_pk_bf16_f32 v145, v158, v159
	v_cvt_pk_bf16_f32 v146, v160, v161
	v_cvt_pk_bf16_f32 v147, v162, v163
	v_pk_mul_f32 v[176:177], v[176:177], v[194:195] op_sel_hi:[1,0]
	v_pk_mul_f32 v[178:179], v[178:179], v[194:195] op_sel_hi:[1,0]
	v_pk_mul_f32 v[180:181], v[180:181], v[194:195] op_sel_hi:[1,0]
	v_pk_mul_f32 v[182:183], v[182:183], v[194:195] op_sel_hi:[1,0]
	v_pk_mul_f32 v[184:185], v[184:185], v[194:195] op_sel_hi:[1,0]
	v_pk_mul_f32 v[186:187], v[186:187], v[194:195] op_sel_hi:[1,0]
	v_pk_mul_f32 v[188:189], v[188:189], v[194:195] op_sel_hi:[1,0]
	v_pk_mul_f32 v[190:191], v[190:191], v[194:195] op_sel_hi:[1,0]
	v_pk_fma_f32 v[176:177], v[0:1], v[176:177], v[8:9]
	v_pk_fma_f32 v[178:179], v[2:3], v[178:179], v[10:11]
	v_pk_fma_f32 v[180:181], v[4:5], v[180:181], v[12:13]
	v_pk_fma_f32 v[182:183], v[6:7], v[182:183], v[14:15]
	v_pk_fma_f32 v[184:185], v[42:43], v[184:185], v[50:51]
	v_pk_fma_f32 v[186:187], v[44:45], v[186:187], v[52:53]
	v_pk_fma_f32 v[188:189], v[46:47], v[188:189], v[54:55]
	v_pk_fma_f32 v[190:191], v[48:49], v[190:191], v[56:57]
	v_cvt_pk_bf16_f32 v168, v176, v177
	v_cvt_pk_bf16_f32 v169, v178, v179
	v_cvt_pk_bf16_f32 v170, v180, v181
	v_cvt_pk_bf16_f32 v171, v182, v183
	v_cvt_pk_bf16_f32 v172, v184, v185
	v_cvt_pk_bf16_f32 v173, v186, v187
	v_cvt_pk_bf16_f32 v174, v188, v189
	v_cvt_pk_bf16_f32 v175, v190, v191
	global_store_dwordx4 v82, v[84:87], s[94:95] offset:0
	global_store_dwordx4 v82, v[88:91], s[94:95] offset:1024
	global_store_dwordx4 v82, v[112:115], s[94:95] offset:2048
	global_store_dwordx4 v82, v[116:119], s[94:95] offset:3072
	s_add_u32 s94, s94, 0x1000
	s_addc_u32 s95, s95, 0
	global_store_dwordx4 v82, v[140:143], s[94:95] offset:0
	global_store_dwordx4 v82, v[144:147], s[94:95] offset:1024
	global_store_dwordx4 v82, v[168:171], s[94:95] offset:2048
	global_store_dwordx4 v82, v[172:175], s[94:95] offset:3072
	s_add_u32 s94, s94, 0x1000
	s_addc_u32 s95, s95, 0
	s_sub_u32 s71, s71, 1
	s_cmp_lg_u32 s71, 0
	s_cbranch_scc1 .Ln2_loop
	s_add_i32 s21, s21, s38
	v_lshl_add_u64 v[20:21], v[20:21], 0, s[10:11]
	s_cmpk_gt_i32 s21, 0xff
	v_lshl_add_u64 v[22:23], v[22:23], 0, s[10:11]
	s_cbranch_scc0 .LBB0_810
